# second-to-last arriver of each XCD issues an advisory L2 write-back at grid barriers
# baseline (speedup 1.0000x reference)
.LBB0_68:
	s_or_b64 exec, exec, s[8:9]
	v_cvt_f32_u32_e32 v3, v10
	s_waitcnt vmcnt(0)
	v_readfirstlane_b32 s6, v2
	v_sub_u32_e32 v2, 0, v10
	v_rcp_iflag_f32_e32 v3, v3
	v_add_u32_e32 v4, s6, v1
	v_mul_f32_e32 v3, 0x4f7ffffe, v3
	v_cvt_u32_f32_e32 v3, v3
	v_mul_lo_u32 v1, v2, v3
	v_mul_hi_u32 v1, v3, v1
	v_add_u32_e32 v1, v3, v1
	v_mul_hi_u32 v1, v4, v1
	v_mul_lo_u32 v2, v1, v10
	v_sub_u32_e32 v2, v4, v2
	v_add_u32_e32 v3, 1, v1
	v_cmp_ge_u32_e32 vcc, v2, v10
	s_nop 1
	v_cndmask_b32_e32 v1, v1, v3, vcc
	v_sub_u32_e32 v3, v2, v10
	v_cndmask_b32_e32 v2, v2, v3, vcc
	v_add_u32_e32 v3, 1, v1
	v_cmp_ge_u32_e32 vcc, v2, v10
	v_add_u32_e32 v2, 1, v4
	s_nop 0
	v_cndmask_b32_e32 v1, v1, v3, vcc
	v_mul_lo_u32 v3, v10, v1
	v_add_u32_e32 v3, v3, v10
	v_cmp_ne_u32_e32 vcc, v2, v3
	s_and_saveexec_b64 s[6:7], vcc
	s_xor_b64 s[6:7], exec, s[6:7]
	s_cbranch_execz .LBB0_82
	v_add_u32_e32 v2, 1, v2
	v_cmp_eq_u32_e32 vcc, v2, v3
	s_cbranch_vccz .Lewb2_skip_0
	buffer_wbl2 sc1
.Lewb2_skip_0:
	v_mov_b32_e32 v2, 0x2000
	global_load_dword v2, v2, s[4:5] offset:1024 sc1
	s_add_u32 s12, s4, 0x2400
	s_addc_u32 s13, s5, 0
	s_waitcnt vmcnt(0)
	v_cmp_eq_u32_e32 vcc, v2, v1
	s_and_saveexec_b64 s[8:9], vcc
	s_cbranch_execz .LBB0_81
	s_add_u32 s10, s46, 0x4200
	s_addc_u32 s11, s47, 0
	s_mov_b32 s28, 1
	s_mov_b64 s[14:15], 0
	v_mov_b32_e32 v2, 0
	s_branch .LBB0_72

.LBB0_177:
	s_or_b64 exec, exec, s[10:11]
	v_cvt_f32_u32_e32 v4, v11
	s_waitcnt vmcnt(0)
	v_readfirstlane_b32 s8, v3
	v_sub_u32_e32 v3, 0, v11
	v_rcp_iflag_f32_e32 v4, v4
	v_add_u32_e32 v5, s8, v2
	v_mul_f32_e32 v4, 0x4f7ffffe, v4
	v_cvt_u32_f32_e32 v4, v4
	v_mul_lo_u32 v2, v3, v4
	v_mul_hi_u32 v2, v4, v2
	v_add_u32_e32 v2, v4, v2
	v_mul_hi_u32 v2, v5, v2
	v_mul_lo_u32 v3, v2, v11
	v_sub_u32_e32 v3, v5, v3
	v_add_u32_e32 v4, 1, v2
	v_cmp_ge_u32_e32 vcc, v3, v11
	s_nop 1
	v_cndmask_b32_e32 v2, v2, v4, vcc
	v_sub_u32_e32 v4, v3, v11
	v_cndmask_b32_e32 v3, v3, v4, vcc
	v_add_u32_e32 v4, 1, v2
	v_cmp_ge_u32_e32 vcc, v3, v11
	v_add_u32_e32 v3, 1, v5
	s_nop 0
	v_cndmask_b32_e32 v2, v2, v4, vcc
	v_mul_lo_u32 v4, v11, v2
	v_add_u32_e32 v4, v4, v11
	v_cmp_ne_u32_e32 vcc, v3, v4
	s_and_saveexec_b64 s[8:9], vcc
	s_xor_b64 s[8:9], exec, s[8:9]
	s_cbranch_execz .LBB0_191
	v_add_u32_e32 v3, 1, v3
	v_cmp_eq_u32_e32 vcc, v3, v4
	s_cbranch_vccz .Lewb2_skip_1
	buffer_wbl2 sc1
.Lewb2_skip_1:
	v_mov_b32_e32 v3, 0x2000
	global_load_dword v3, v3, s[6:7] offset:1024 sc1
	s_add_u32 s14, s6, 0x2400
	s_addc_u32 s15, s7, 0
	s_waitcnt vmcnt(0)
	v_cmp_eq_u32_e32 vcc, v3, v2
	s_and_saveexec_b64 s[10:11], vcc
	s_cbranch_execz .LBB0_190
	s_add_u32 s12, s46, 0x4200
	s_addc_u32 s13, s47, 0
	s_mov_b32 s34, 1
	s_mov_b64 s[16:17], 0
	v_mov_b32_e32 v3, 0
	s_branch .LBB0_181

.LBB0_386:
	s_or_b64 exec, exec, s[12:13]
	v_cvt_f32_u32_e32 v4, v11
	s_waitcnt vmcnt(0)
	v_readfirstlane_b32 s10, v3
	v_sub_u32_e32 v3, 0, v11
	v_rcp_iflag_f32_e32 v4, v4
	v_add_u32_e32 v5, s10, v2
	v_mul_f32_e32 v4, 0x4f7ffffe, v4
	v_cvt_u32_f32_e32 v4, v4
	v_mul_lo_u32 v2, v3, v4
	v_mul_hi_u32 v2, v4, v2
	v_add_u32_e32 v2, v4, v2
	v_mul_hi_u32 v2, v5, v2
	v_mul_lo_u32 v3, v2, v11
	v_sub_u32_e32 v3, v5, v3
	v_add_u32_e32 v4, 1, v2
	v_cmp_ge_u32_e32 vcc, v3, v11
	s_nop 1
	v_cndmask_b32_e32 v2, v2, v4, vcc
	v_sub_u32_e32 v4, v3, v11
	v_cndmask_b32_e32 v3, v3, v4, vcc
	v_add_u32_e32 v4, 1, v2
	v_cmp_ge_u32_e32 vcc, v3, v11
	v_add_u32_e32 v3, 1, v5
	s_nop 0
	v_cndmask_b32_e32 v2, v2, v4, vcc
	v_mul_lo_u32 v4, v11, v2
	v_add_u32_e32 v4, v4, v11
	v_cmp_ne_u32_e32 vcc, v3, v4
	s_and_saveexec_b64 s[10:11], vcc
	s_xor_b64 s[10:11], exec, s[10:11]
	s_cbranch_execz .LBB0_400
	v_add_u32_e32 v3, 1, v3
	v_cmp_eq_u32_e32 vcc, v3, v4
	s_cbranch_vccz .Lewb2_skip_2
	buffer_wbl2 sc1
.Lewb2_skip_2:
	v_mov_b32_e32 v3, 0x2000
	global_load_dword v3, v3, s[6:7] offset:1024 sc1
	s_add_u32 s16, s6, 0x2400
	s_addc_u32 s17, s7, 0
	s_waitcnt vmcnt(0)
	v_cmp_eq_u32_e32 vcc, v3, v2
	s_and_saveexec_b64 s[12:13], vcc
	s_cbranch_execz .LBB0_399
	s_add_u32 s14, s46, 0x4200
	s_addc_u32 s15, s47, 0
	s_mov_b32 s36, 1
	s_mov_b64 s[18:19], 0
	v_mov_b32_e32 v3, 0
	s_branch .LBB0_390

.LBB0_620:
	s_or_b64 exec, exec, s[14:15]
	v_cvt_f32_u32_e32 v4, v11
	s_waitcnt vmcnt(0)
	v_readfirstlane_b32 s12, v3
	v_sub_u32_e32 v3, 0, v11
	v_rcp_iflag_f32_e32 v4, v4
	v_add_u32_e32 v5, s12, v2
	v_mul_f32_e32 v4, 0x4f7ffffe, v4
	v_cvt_u32_f32_e32 v4, v4
	v_mul_lo_u32 v2, v3, v4
	v_mul_hi_u32 v2, v4, v2
	v_add_u32_e32 v2, v4, v2
	v_mul_hi_u32 v2, v5, v2
	v_mul_lo_u32 v3, v2, v11
	v_sub_u32_e32 v3, v5, v3
	v_add_u32_e32 v4, 1, v2
	v_cmp_ge_u32_e32 vcc, v3, v11
	s_nop 1
	v_cndmask_b32_e32 v2, v2, v4, vcc
	v_sub_u32_e32 v4, v3, v11
	v_cndmask_b32_e32 v3, v3, v4, vcc
	v_add_u32_e32 v4, 1, v2
	v_cmp_ge_u32_e32 vcc, v3, v11
	v_add_u32_e32 v3, 1, v5
	s_nop 0
	v_cndmask_b32_e32 v2, v2, v4, vcc
	v_mul_lo_u32 v4, v11, v2
	v_add_u32_e32 v4, v4, v11
	v_cmp_ne_u32_e32 vcc, v3, v4
	s_and_saveexec_b64 s[12:13], vcc
	s_xor_b64 s[12:13], exec, s[12:13]
	s_cbranch_execz .LBB0_634
	v_add_u32_e32 v3, 1, v3
	v_cmp_eq_u32_e32 vcc, v3, v4
	s_cbranch_vccz .Lewb2_skip_3
	buffer_wbl2 sc1
.Lewb2_skip_3:
	v_mov_b32_e32 v3, 0x2000
	global_load_dword v3, v3, s[10:11] offset:1024 sc1
	s_add_u32 s18, s10, 0x2400
	s_addc_u32 s19, s11, 0
	s_waitcnt vmcnt(0)
	v_cmp_eq_u32_e32 vcc, v3, v2
	s_and_saveexec_b64 s[14:15], vcc
	s_cbranch_execz .LBB0_633
	s_add_u32 s16, s46, 0x4200
	s_addc_u32 s17, s47, 0
	s_mov_b32 s38, 1
	s_mov_b64 s[20:21], 0
	v_mov_b32_e32 v3, 0
	s_branch .LBB0_624

.Lewb2_skip_4:
	v_mov_b32_e32 v3, 0x2000
	global_load_dword v3, v3, s[8:9] offset:1024 sc1
	s_add_u32 s16, s8, 0x2400
	s_addc_u32 s17, s9, 0
	s_waitcnt vmcnt(0)
	v_cmp_eq_u32_e32 vcc, v3, v2
	s_and_saveexec_b64 s[12:13], vcc
	s_cbranch_execz .LBB0_790
	s_add_u32 s14, s46, 0x4200
	s_addc_u32 s15, s47, 0
	s_mov_b32 s34, 1
	s_mov_b64 s[18:19], 0
	v_mov_b32_e32 v3, 0
	s_branch .LBB0_781

.Lewb2_skip_5:
	v_mov_b32_e32 v3, 0x2000
	global_load_dword v3, v3, s[8:9] offset:1024 sc1
	s_add_u32 s16, s8, 0x2400
	s_addc_u32 s17, s9, 0
	s_waitcnt vmcnt(0)
	v_cmp_eq_u32_e32 vcc, v3, v2
	s_and_saveexec_b64 s[12:13], vcc
	s_cbranch_execz .LBB0_913
	s_add_u32 s14, s46, 0x4200
	s_addc_u32 s15, s47, 0
	s_mov_b32 s30, 1
	s_mov_b64 s[18:19], 0
	v_mov_b32_e32 v3, 0
	s_branch .LBB0_904

.Lewb2_skip_9:
	v_mov_b32_e32 v3, 0x2000
	global_load_dword v3, v3, s[4:5] offset:1024 sc1
	s_add_u32 s14, s4, 0x2400
	s_addc_u32 s15, s5, 0
	s_waitcnt vmcnt(0)
	v_cmp_eq_u32_e32 vcc, v3, v2
	s_and_saveexec_b64 s[10:11], vcc
	s_cbranch_execz .LBB0_2058
	s_add_u32 s12, s46, 0x4200
	s_addc_u32 s13, s47, 0
	s_mov_b32 s28, 1
	s_mov_b64 s[16:17], 0
	v_mov_b32_e32 v3, 0
	s_branch .LBB0_2049
